# E4g + waves 4-7 raise s_setprio 1 at the start of their out-of-line LDS-DMA issue block (MLA loop)
# speedup vs baseline: 1.0052x; 1.0052x over previous
.Lmla_dma1:
	s_setprio 1
	s_lshl_b64 s[14:15], s[50:51], 13
	s_add_u32 s44, s80, s14
	s_addc_u32 s45, s81, s15
	s_add_u32 s14, s78, s14
	s_addc_u32 s15, s79, s15
	s_cmp_lg_u32 0, -1
	s_cselect_b32 s16, 0, 0
	s_add_i32 s16, s16, s41
	v_lshl_add_u64 v[80:81], s[44:45], 0, v[128:129]
	s_add_i32 s23, s16, 0x4000
	s_mov_b32 m0, s23
	s_nop 0
	global_load_lds_dwordx4 v[80:81], off
	v_lshl_add_u64 v[80:81], s[44:45], 0, v[192:193]
	s_add_i32 s23, s16, 0x6000
	s_mov_b32 m0, s23
	s_nop 0
	global_load_lds_dwordx4 v[80:81], off
	v_lshl_add_u64 v[80:81], s[14:15], 0, v[190:191]
	s_add_i32 s23, s16, 0xc000
	s_mov_b32 m0, s23
	s_nop 0
	global_load_lds_dwordx4 v[80:81], off
	v_lshl_add_u64 v[80:81], s[14:15], 0, v[188:189]
	s_add_i32 s14, s16, 0xe000
	s_mov_b32 m0, s14
	s_nop 0
	global_load_lds_dwordx4 v[80:81], off
	s_lshl_b64 s[14:15], s[50:51], 7
	v_lshl_add_u64 v[80:81], v[194:195], 0, s[14:15]
	s_add_i32 s16, s16, 0x12800
	s_mov_b32 m0, s16
	s_nop 0
	global_load_lds_dwordx4 v[80:81], off
	s_lshl_b64 s[14:15], s[50:51], 13
	s_add_u32 s44, s80, s14
	s_addc_u32 s45, s81, s15
	s_add_u32 s14, s78, s14
	s_addc_u32 s15, s79, s15
	s_sub_u32 s44, s44, 0x20000
	s_subb_u32 s45, s45, 0
	s_sub_u32 s14, s14, 0x20000
	s_subb_u32 s15, s15, 0
	s_add_i32 s16, s41, 0xfffff000
	v_lshl_add_u64 v[80:81], s[44:45], 0, v[128:129]
	s_add_i32 s23, s16, 0x4000
	s_mov_b32 m0, s23
	s_nop 0
	global_load_lds_dwordx4 v[80:81], off
	v_lshl_add_u64 v[80:81], s[44:45], 0, v[192:193]
	s_add_i32 s23, s16, 0x6000
	s_mov_b32 m0, s23
	s_nop 0
	global_load_lds_dwordx4 v[80:81], off
	v_lshl_add_u64 v[80:81], s[14:15], 0, v[190:191]
	s_add_i32 s23, s16, 0xc000
	s_mov_b32 m0, s23
	s_nop 0
	global_load_lds_dwordx4 v[80:81], off
	v_lshl_add_u64 v[80:81], s[14:15], 0, v[188:189]
	s_add_i32 s23, s16, 0xe000
	s_mov_b32 m0, s23
	s_nop 0
	global_load_lds_dwordx4 v[80:81], off
	s_lshl_b64 s[14:15], s[50:51], 7
	s_sub_u32 s14, s14, 0x1000
	s_subb_u32 s15, s15, 0
	v_lshl_add_u64 v[80:81], v[194:195], 0, s[14:15]
	s_add_i32 s23, s16, 0x12800
	s_mov_b32 m0, s23
	s_nop 0
	global_load_lds_dwordx4 v[80:81], off
	s_branch .Lmla_dma1_ret
.Lmla_dma2:
	s_setprio 1
	s_mov_b32 s83, s51
	s_lshl_b64 s[14:15], s[82:83], 13
	s_add_u32 s44, s80, s14
	s_addc_u32 s45, s81, s15
	s_add_u32 s14, s78, s14
	s_addc_u32 s15, s79, s15
	v_lshl_add_u64 v[96:97], s[44:45], 0, v[128:129]
	s_mov_b32 m0, s97
	s_nop 0
	global_load_lds_dwordx4 v[96:97], off
	s_cmp_lg_u32 0, -1
	s_cselect_b32 s16, 0, 0
	s_add_i32 s16, s16, s41
	v_lshl_add_u64 v[96:97], s[44:45], 0, v[192:193]
	s_add_i32 s23, s16, 0x2000
	s_mov_b32 m0, s23
	s_nop 0
	global_load_lds_dwordx4 v[96:97], off
	v_lshl_add_u64 v[96:97], s[14:15], 0, v[190:191]
	s_mov_b32 m0, s40
	s_nop 0
	global_load_lds_dwordx4 v[96:97], off
	v_lshl_add_u64 v[96:97], s[14:15], 0, v[188:189]
	s_add_i32 s16, s16, 0xa000
	s_mov_b32 m0, s16
	s_nop 0
	global_load_lds_dwordx4 v[96:97], off
	s_lshl_b64 s[14:15], s[82:83], 7
	v_lshl_add_u64 v[96:97], v[194:195], 0, s[14:15]
	s_mov_b32 m0, s46
	s_nop 0
	global_load_lds_dwordx4 v[96:97], off
	s_lshl_b64 s[14:15], s[82:83], 13
	s_add_u32 s44, s80, s14
	s_addc_u32 s45, s81, s15
	s_add_u32 s14, s78, s14
	s_addc_u32 s15, s79, s15
	s_sub_u32 s44, s44, 0x20000
	s_subb_u32 s45, s45, 0
	s_sub_u32 s14, s14, 0x20000
	s_subb_u32 s15, s15, 0
	s_add_i32 s16, s41, 0xfffff000
	v_lshl_add_u64 v[96:97], s[44:45], 0, v[128:129]
	s_add_i32 s23, s97, 0xfffff000
	s_mov_b32 m0, s23
	s_nop 0
	global_load_lds_dwordx4 v[96:97], off
	v_lshl_add_u64 v[96:97], s[44:45], 0, v[192:193]
	s_add_i32 s23, s16, 0x2000
	s_mov_b32 m0, s23
	s_nop 0
	global_load_lds_dwordx4 v[96:97], off
	v_lshl_add_u64 v[96:97], s[14:15], 0, v[190:191]
	s_add_i32 s23, s40, 0xfffff000
	s_mov_b32 m0, s23
	s_nop 0
	global_load_lds_dwordx4 v[96:97], off
	v_lshl_add_u64 v[96:97], s[14:15], 0, v[188:189]
	s_add_i32 s23, s16, 0xa000
	s_mov_b32 m0, s23
	s_nop 0
	global_load_lds_dwordx4 v[96:97], off
	s_lshl_b64 s[14:15], s[82:83], 7
	s_sub_u32 s14, s14, 0x1000
	s_subb_u32 s15, s15, 0
	v_lshl_add_u64 v[96:97], v[194:195], 0, s[14:15]
	s_add_i32 s23, s46, 0xfffff000
	s_mov_b32 m0, s23
	s_nop 0
	global_load_lds_dwordx4 v[96:97], off
	s_branch .LBB0_844
